# merge gemm_big k-loop ported to the 3-stage LDS ring (LDS-DMA even k-steps + register-staged odd k-steps), same as inproj
# speedup vs baseline: 1.0683x; 1.0432x over previous
; DI int otid() { int t; asm volatile("v_mov_b32 %0, %1" : "=v"(t) : "v"((int)threadIdx.x)); __builtin_assume(t >= 0 && t < 256); return t; }
; #define BLOADG(kt) do { \
;     _Pragma("unroll") for (int i = 0; i < 2; ++i) ra[i] = *(const u32x4*)(ap + (size_t)(64 * i) * lda + (kt) * 32); \
;     _Pragma("unroll") for (int i = 0; i < 4; ++i) rb[i] = *(const u32x4*)(bp + (size_t)((i & 1) * s1 + (i >> 1) * s2) * ldb + (kt) * 32); } while (0)
; #define BSTOREG(st) do { \
;     _Pragma("unroll") for (int i = 0; i < 2; ++i) *(u32x4*)(sA + (st) * BGA + so + 64 * i * 32) = ra[i]; \
;     _Pragma("unroll") for (int i = 0; i < 4; ++i) *(u32x4*)(sB + (st) * BGB + so + 64 * i * 32) = rb[i]; } while (0)
;   bf16_t* sA = (bf16_t*)smem; bf16_t* sB = sA + 2 * BGA;
;   const int tid = otid(), lane = tid & 63, wid = tid >> 6;
;   const int wm = wid >> 1, wn = wid & 1, fr = lane & 15, fq = lane >> 4;
;   const int nk = K >> 5;
;   const bf16_t* ap = A + (size_t)(tid >> 2) * lda + (tid & 3) * 8;
;   const bf16_t* bp = Bt + (size_t)(brow >= 0 ? brow : (tid >> 2)) * ldb + (tid & 3) * 8;
;   const int so = (tid >> 2) * 32 + (((tid & 3) ^ (((tid >> 5) & 1) << 1)) * 8);
;   const int fo = fr * 32 + ((fq ^ (((fr >> 3) & 1) << 1)) * 8);
;   u32x4 ra[2], rb[4];
;     ...
;   __syncthreads();
;   BLOADG(0); BSTOREG(0);
;   if (nk > 1) BLOADG(1);
;   __syncthreads();
; DI void merge_tile(const Params& p, int l, int tile, char* smem) {
;     ...
;     gemm_big(accG, P_XN + (size_t)mt * 128 * 1024, 1024, P_WMT + ((size_t)l * 4096 + nt * 64) * 1024, 1024, 1024, smem, 2048, 32,
;              (otid() >> 7) * 1024 + ((otid() >> 2) & 31));
.LBB0_44:
	s_ashr_i32 s29, s26, 4
	s_and_b32 s0, s29, 0x1ffffff8
	v_readlane_b32 s1, v253, 54
	s_or_b32 s0, s0, s1
	s_lshl_b32 s0, s0, 3
	s_and_b32 s1, s26, 7
	s_or_b32 s1, s0, s1
	s_lshl_b32 s6, s26, 5
	s_lshl_b32 s1, s1, 7
	s_and_b32 s6, s6, 0xf00
	s_and_b32 s27, s1, 0x7f80
	s_and_b32 s11, s25, 7
	s_add_i32 s0, s0, s6
	s_lshl_b32 s1, s27, 11
	s_add_u32 s6, s31, s1
	s_addc_u32 s7, s30, 0
	s_ashr_i32 s28, s0, 2
	s_andn2_b32 s28, s28, 63
	s_ashr_i32 s1, s28, 31
	v_mov_b32 v0, v188
	s_add_u32 s0, s28, s24
	v_lshlrev_b32_e32 v0, 3, v0
	v_mov_b32 v2, v188
	s_addc_u32 s1, s1, 0
	v_and_b32_e32 v0, 0x400, v0
	v_lshrrev_b32_e32 v2, 2, v2
	v_mov_b32 v27, v188
	s_lshl_b64 s[12:13], s[0:1], 11
	v_lshrrev_b32_e32 v26, 2, v27
	v_readlane_b32 s22, v253, 22
	v_and_or_b32 v4, v2, 31, v0
	v_lshlrev_b32_e32 v0, 11, v26
	v_and_b32_e32 v42, 3, v27
	s_add_u32 s22, s22, s12
	v_readlane_b32 s23, v253, 23
	v_lshl_add_u64 v[2:3], s[6:7], 0, v[0:1]
	v_lshlrev_b32_e32 v0, 4, v42
	s_addc_u32 s23, s23, s13
	v_lshl_add_u64 v[28:29], v[2:3], 0, v[0:1]
	v_lshlrev_b32_e32 v30, 11, v4
	v_mov_b32_e32 v31, v1
	v_lshl_add_u64 v[2:3], s[22:23], 0, v[30:31]
	v_add_co_u32_e32 v34, vcc, s77, v28
	v_lshl_add_u64 v[32:33], v[2:3], 0, v[0:1]
	s_nop 0
	v_addc_co_u32_e32 v35, vcc, 0, v29, vcc
	s_mov_b32 s6, 0x400000
	v_add_co_u32_e32 v36, vcc, s6, v32
	s_mov_b32 s6, 0x10000
	s_nop 0
	v_addc_co_u32_e32 v37, vcc, 0, v33, vcc
	v_add_co_u32_e32 v38, vcc, s6, v32
	s_barrier
	v_lshrrev_b32_e32 v227, 6, v188
	v_lshlrev_b32_e32 v227, 10, v227
	v_lshrrev_b32_e32 v228, 4, v188
	v_and_b32_e32 v219, 3, v188
	v_and_b32_e32 v228, 2, v228
	v_xor_b32_e32 v223, v228, v219
	v_readfirstlane_b32 s100, v227
	v_lshrrev_b32_e32 v218, 2, v188
	v_lshlrev_b32_e32 v218, 11, v218
	v_lshl_or_b32 v218, v223, 4, v218
	v_add_u32_e32 v219, 0x20000, v218
	v_lshrrev_b32_e32 v220, 2, v188
	v_lshlrev_b32_e32 v221, 3, v188
	v_and_b32_e32 v220, 31, v220
	v_and_b32_e32 v221, 0x400, v221
	v_or_b32_e32 v220, v220, v221
	v_lshlrev_b32_e32 v220, 11, v220
	v_lshl_or_b32 v220, v223, 4, v220
	v_add_u32_e32 v221, 0x400000, v220
	v_add_u32_e32 v222, 0x10000, v220
	v_add_u32_e32 v223, 0x410000, v220
	s_mov_b32 m0, s100
	s_lshl_b32 s100, s27, 11
	s_add_u32 s100, s31, s100
	s_addc_u32 s101, s30, 0
	s_nop 0
	global_load_lds_dwordx4 v218, s[100:101]
	s_add_u32 m0, m0, 0x1fc0
	s_nop 0
	global_load_lds_dwordx4 v218, s[100:101] offset:64
	s_sub_u32 m0, m0, 0xfc0
	s_nop 0
	global_load_lds_dwordx4 v219, s[100:101]
	s_add_u32 m0, m0, 0x1fc0
	s_nop 0
	global_load_lds_dwordx4 v219, s[100:101] offset:64
	s_add_u32 m0, m0, 0x1040
	s_nop 0
	global_load_lds_dwordx4 v220, s[22:23]
	s_add_u32 m0, m0, 0x3fc0
	s_nop 0
	global_load_lds_dwordx4 v220, s[22:23] offset:64
	s_sub_u32 m0, m0, 0x2fc0
	s_nop 0
	global_load_lds_dwordx4 v221, s[22:23]
	s_add_u32 m0, m0, 0x3fc0
	s_nop 0
	global_load_lds_dwordx4 v221, s[22:23] offset:64
	s_sub_u32 m0, m0, 0x2fc0
	s_nop 0
	global_load_lds_dwordx4 v222, s[22:23]
	s_add_u32 m0, m0, 0x3fc0
	s_nop 0
	global_load_lds_dwordx4 v222, s[22:23] offset:64
	s_sub_u32 m0, m0, 0x2fc0
	s_nop 0
	global_load_lds_dwordx4 v223, s[22:23]
	s_add_u32 m0, m0, 0x3fc0
	s_nop 0
	global_load_lds_dwordx4 v223, s[22:23] offset:64
	s_add_u32 s100, s100, 0x80
	s_addc_u32 s101, s101, 0
	s_add_u32 s22, s22, 0x80
	s_addc_u32 s23, s23, 0
	s_sub_u32 m0, m0, 0x3fc0
	s_nop 0
	v_addc_co_u32_e32 v39, vcc, 0, v33, vcc
	s_mov_b32 s6, 0x410000
	v_add_co_u32_e32 v40, vcc, s6, v32
	v_addc_co_u32_e32 v41, vcc, 0, v33, vcc
	s_lshl_b32 s6, s29, 3
	v_lshrrev_b32_e32 v43, 4, v27
	v_lshlrev_b32_e32 v45, 6, v27
	v_and_b32_e32 v46, 2, v26
	v_or_b32_e32 v28, s12, v0
	s_and_b32 s6, s6, 0xc0
	v_readlane_b32 s12, v253, 55
	v_bitop3_b32 v42, v43, v42, 2 bitop3:0x6c
	v_lshlrev_b32_e32 v47, 6, v26
	v_and_b32_e32 v45, 0x3c0, v45
	v_bitop3_b32 v43, v43, v46, 3 bitop3:0x6c
	s_or_b32 s6, s12, s6
	v_lshlrev_b32_e32 v44, 5, v27
	v_lshlrev_b32_e32 v27, 7, v27
	v_lshl_or_b32 v164, v42, 4, v47
	v_lshl_or_b32 v42, v43, 4, v45
	s_add_i32 s6, s6, s11
	v_and_or_b32 v162, v27, s34, v42
	s_and_b32 s6, s6, 0xff
	v_mov_b32_e32 v27, v1
	s_lshl_b32 s94, s6, 18
	v_mov_b32_e32 v29, s13
	v_lshl_add_u64 v[28:29], v[28:29], 0, v[30:31]
	s_mov_b32 s7, 0
	v_and_or_b32 v163, v44, s85, v42
	v_lshl_add_u64 v[158:159], s[58:59], 0, v[28:29]
	v_lshlrev_b64 v[2:3], 11, v[26:27]
	v_lshl_add_u64 v[2:3], s[94:95], 0, v[2:3]
	v_or_b32_e32 v2, v2, v0
	v_lshl_add_u64 v[160:161], s[58:59], 0, v[2:3]
	v_mov_b32_e32 v2, 0
	v_mov_b32_e32 v3, v2
	v_mov_b32_e32 v4, v2
	v_mov_b32_e32 v5, v2
	v_mov_b32_e32 v6, v2
	v_mov_b32_e32 v7, v2
	v_mov_b32_e32 v8, v2
	v_mov_b32_e32 v9, v2
	v_mov_b32_e32 v10, v2
	v_mov_b32_e32 v11, v2
	v_mov_b32_e32 v12, v2
	v_mov_b32_e32 v13, v2
	v_mov_b32_e32 v14, v2
	v_mov_b32_e32 v15, v2
	v_mov_b32_e32 v16, v2
	v_mov_b32_e32 v17, v2
	v_mov_b32_e32 v42, v2
	v_mov_b32_e32 v43, v2
	v_mov_b32_e32 v44, v2
	v_mov_b32_e32 v45, v2
	v_mov_b32_e32 v50, v2
	v_mov_b32_e32 v51, v2
	v_mov_b32_e32 v52, v2
	v_mov_b32_e32 v53, v2
	v_mov_b32_e32 v58, v2
	v_mov_b32_e32 v59, v2
	v_mov_b32_e32 v60, v2
	v_mov_b32_e32 v61, v2
	v_mov_b32_e32 v62, v2
	v_mov_b32_e32 v63, v2
	v_mov_b32_e32 v64, v2
	v_mov_b32_e32 v65, v2
	v_mov_b32_e32 v18, v2
	v_mov_b32_e32 v19, v2
	v_mov_b32_e32 v20, v2
	v_mov_b32_e32 v21, v2
	v_mov_b32_e32 v22, v2
	v_mov_b32_e32 v23, v2
	v_mov_b32_e32 v24, v2
	v_mov_b32_e32 v25, v2
	v_mov_b32_e32 v26, v2
	v_mov_b32_e32 v27, v2
	v_mov_b32_e32 v28, v2
	v_mov_b32_e32 v29, v2
	v_mov_b32_e32 v30, v2
	v_mov_b32_e32 v31, v2
	v_mov_b32_e32 v32, v2
	v_mov_b32_e32 v33, v2
	v_mov_b32_e32 v74, v2
	v_mov_b32_e32 v75, v2
	v_mov_b32_e32 v76, v2
	v_mov_b32_e32 v77, v2
	v_mov_b32_e32 v82, v2
	v_mov_b32_e32 v83, v2
; #define BLOADG(kt) do { \
;     _Pragma("unroll") for (int i = 0; i < 2; ++i) ra[i] = *(const u32x4*)(ap + (size_t)(64 * i) * lda + (kt) * 32); \
;     _Pragma("unroll") for (int i = 0; i < 4; ++i) rb[i] = *(const u32x4*)(bp + (size_t)((i & 1) * s1 + (i >> 1) * s2) * ldb + (kt) * 32); } while (0)
; #define BSTOREG(st) do { \
;     _Pragma("unroll") for (int i = 0; i < 2; ++i) *(u32x4*)(sA + (st) * BGA + so + 64 * i * 32) = ra[i]; \
;     _Pragma("unroll") for (int i = 0; i < 4; ++i) *(u32x4*)(sB + (st) * BGB + so + 64 * i * 32) = rb[i]; } while (0)
;     ...
;   for (int kt = 0; kt < nk; ++kt) {
;     const int cur = kt & 1;
;     if (kt + 1 < nk) { BSTOREG(cur ^ 1); if (kt + 2 < nk) BLOADG(kt + 2); }
;     const bf16_t* cA = sA + cur * BGA + (wm * 64) * 32 + fo; const bf16_t* cB = sB + cur * BGB + (wn * 128) * 32 + fo;
;     bf16x8 af[4];
; #pragma unroll
;     for (int mi = 0; mi < 4; ++mi) af[mi] = *(const bf16x8*)(cA + mi * 16 * 32);
; #pragma unroll
;     for (int nh = 0; nh < 2; ++nh) {
;       bf16x8 bfr[4];
; #pragma unroll
;       for (int ni = 0; ni < 4; ++ni) bfr[ni] = *(const bf16x8*)(cB + (nh * 4 + ni) * 16 * 32);
; #pragma unroll
;       for (int mi = 0; mi < 4; ++mi)
; #pragma unroll
;         for (int ni = 0; ni < 4; ++ni) acc[mi][nh * 4 + ni] = __builtin_amdgcn_mfma_f32_16x16x32_bf16(bfr[ni], af[mi], acc[mi][nh * 4 + ni], 0, 0, 0);
;     }
; DI void zero_acc8(f32x4 (&acc)[4][8]) {
; #pragma unroll
;   for (int mi = 0; mi < 4; ++mi)
; #pragma unroll
;     for (int ni = 0; ni < 8; ++ni) acc[mi][ni] = f32x4{0.f, 0.f, 0.f, 0.f};
	v_mov_b32_e32 v84, v2
	v_mov_b32_e32 v85, v2
	v_mov_b32_e32 v90, v2
	v_mov_b32_e32 v91, v2
	v_mov_b32_e32 v92, v2
	v_mov_b32_e32 v93, v2
	v_mov_b32_e32 v94, v2
	v_mov_b32_e32 v95, v2
	v_mov_b32_e32 v96, v2
	v_mov_b32_e32 v97, v2
	v_mov_b32_e32 v34, v2
	v_mov_b32_e32 v35, v2
	v_mov_b32_e32 v36, v2
	v_mov_b32_e32 v37, v2
	v_mov_b32_e32 v38, v2
	v_mov_b32_e32 v39, v2
	v_mov_b32_e32 v40, v2
	v_mov_b32_e32 v41, v2
	v_mov_b32_e32 v46, v2
	v_mov_b32_e32 v47, v2
	v_mov_b32_e32 v48, v2
	v_mov_b32_e32 v49, v2
	v_mov_b32_e32 v54, v2
	v_mov_b32_e32 v55, v2
	v_mov_b32_e32 v56, v2
	v_mov_b32_e32 v57, v2
	v_mov_b32_e32 v98, v2
	v_mov_b32_e32 v99, v2
	v_mov_b32_e32 v100, v2
	v_mov_b32_e32 v101, v2
	v_mov_b32_e32 v102, v2
	v_mov_b32_e32 v103, v2
	v_mov_b32_e32 v104, v2
	v_mov_b32_e32 v105, v2
	v_mov_b32_e32 v106, v2
	v_mov_b32_e32 v107, v2
	v_mov_b32_e32 v108, v2
	v_mov_b32_e32 v109, v2
	v_mov_b32_e32 v110, v2
	v_mov_b32_e32 v111, v2
	v_mov_b32_e32 v112, v2
	v_mov_b32_e32 v113, v2
	v_mov_b32_e32 v66, v2
	v_mov_b32_e32 v67, v2
	v_mov_b32_e32 v68, v2
	v_mov_b32_e32 v69, v2
	v_mov_b32_e32 v70, v2
	v_mov_b32_e32 v71, v2
	v_mov_b32_e32 v72, v2
	v_mov_b32_e32 v73, v2
	v_mov_b32_e32 v78, v2
	v_mov_b32_e32 v79, v2
	v_mov_b32_e32 v80, v2
	v_mov_b32_e32 v81, v2
	v_mov_b32_e32 v86, v2
	v_mov_b32_e32 v87, v2
	v_mov_b32_e32 v88, v2
	v_mov_b32_e32 v89, v2
	v_mov_b32_e32 v114, v2
	v_mov_b32_e32 v115, v2
	v_mov_b32_e32 v116, v2
	v_mov_b32_e32 v117, v2
	v_mov_b32_e32 v118, v2
	v_mov_b32_e32 v119, v2
	v_mov_b32_e32 v120, v2
	v_mov_b32_e32 v121, v2
	v_mov_b32_e32 v122, v2
	v_mov_b32_e32 v123, v2
	v_mov_b32_e32 v124, v2
	v_mov_b32_e32 v125, v2
	v_mov_b32_e32 v126, v2
	v_mov_b32_e32 v127, v2
	v_mov_b32_e32 v128, v2
	v_mov_b32_e32 v129, v2
	v_add_u32_e32 v224, 0x8000, v163
	v_lshlrev_b32_e32 v225, 4, v188
	v_add_u32_e32 v226, 0x8000, v225
	s_waitcnt vmcnt(0)
	s_barrier
.LBB0_45:
	ds_read_b128 v[166:169], v163 offset:0
	ds_read_b128 v[170:173], v163 offset:1024
	ds_read_b128 v[174:177], v163 offset:2048
	ds_read_b128 v[178:181], v163 offset:3072
	ds_read_b128 v[182:185], v162 offset:16384
	ds_read_b128 v[206:209], v162 offset:17408
	ds_read_b128 v[210:213], v162 offset:18432
	ds_read_b128 v[214:217], v162 offset:19456
	s_waitcnt lgkmcnt(7)
	s_waitcnt lgkmcnt(3)
	v_mfma_f32_16x16x32_bf16 v[126:129], v[182:185], v[166:169], v[126:129]
	v_mfma_f32_16x16x32_bf16 v[110:113], v[182:185], v[170:173], v[110:113]
	v_mfma_f32_16x16x32_bf16 v[94:97], v[182:185], v[174:177], v[94:97]
	v_mfma_f32_16x16x32_bf16 v[62:65], v[182:185], v[178:181], v[62:65]
	ds_read_b128 v[182:185], v162 offset:20480
	s_add_u32 m0, m0, 0x9400
	s_nop 0
	global_load_lds_dwordx4 v218, s[100:101]
	global_load_dwordx4 v[134:137], v218, s[100:101] offset:64
	s_waitcnt lgkmcnt(3)
	v_mfma_f32_16x16x32_bf16 v[122:125], v[206:209], v[166:169], v[122:125]
	v_mfma_f32_16x16x32_bf16 v[106:109], v[206:209], v[170:173], v[106:109]
	v_mfma_f32_16x16x32_bf16 v[90:93], v[206:209], v[174:177], v[90:93]
	v_mfma_f32_16x16x32_bf16 v[58:61], v[206:209], v[178:181], v[58:61]
	ds_read_b128 v[206:209], v162 offset:21504
	s_add_u32 m0, m0, 0x1000
	s_nop 0
	global_load_lds_dwordx4 v219, s[100:101]
	global_load_dwordx4 v[130:133], v219, s[100:101] offset:64
	s_waitcnt lgkmcnt(3)
	v_mfma_f32_16x16x32_bf16 v[118:121], v[210:213], v[166:169], v[118:121]
	v_mfma_f32_16x16x32_bf16 v[102:105], v[210:213], v[170:173], v[102:105]
	v_mfma_f32_16x16x32_bf16 v[82:85], v[210:213], v[174:177], v[82:85]
	v_mfma_f32_16x16x32_bf16 v[50:53], v[210:213], v[178:181], v[50:53]
	ds_read_b128 v[210:213], v162 offset:22528
	s_sub_u32 m0, m0, 0x5400
	s_nop 0
	global_load_lds_dwordx4 v220, s[22:23]
	global_load_dwordx4 v[146:149], v220, s[22:23] offset:64
	s_waitcnt lgkmcnt(3)
	v_mfma_f32_16x16x32_bf16 v[114:117], v[214:217], v[166:169], v[114:117]
	v_mfma_f32_16x16x32_bf16 v[98:101], v[214:217], v[170:173], v[98:101]
	v_mfma_f32_16x16x32_bf16 v[74:77], v[214:217], v[174:177], v[74:77]
	v_mfma_f32_16x16x32_bf16 v[42:45], v[214:217], v[178:181], v[42:45]
	ds_read_b128 v[214:217], v162 offset:23552
	s_add_u32 m0, m0, 0x1000
	s_nop 0
	global_load_lds_dwordx4 v221, s[22:23]
	global_load_dwordx4 v[142:145], v221, s[22:23] offset:64
	s_waitcnt lgkmcnt(3)
	v_mfma_f32_16x16x32_bf16 v[86:89], v[182:185], v[166:169], v[86:89]
	v_mfma_f32_16x16x32_bf16 v[54:57], v[182:185], v[170:173], v[54:57]
	v_mfma_f32_16x16x32_bf16 v[30:33], v[182:185], v[174:177], v[30:33]
	v_mfma_f32_16x16x32_bf16 v[14:17], v[182:185], v[178:181], v[14:17]
	s_add_u32 m0, m0, 0x1000
	s_nop 0
	global_load_lds_dwordx4 v222, s[22:23]
	global_load_dwordx4 v[138:141], v222, s[22:23] offset:64
	s_waitcnt lgkmcnt(2)
	v_mfma_f32_16x16x32_bf16 v[78:81], v[206:209], v[166:169], v[78:81]
	v_mfma_f32_16x16x32_bf16 v[46:49], v[206:209], v[170:173], v[46:49]
	v_mfma_f32_16x16x32_bf16 v[26:29], v[206:209], v[174:177], v[26:29]
	v_mfma_f32_16x16x32_bf16 v[10:13], v[206:209], v[178:181], v[10:13]
	s_add_u32 m0, m0, 0x1000
	s_nop 0
	global_load_lds_dwordx4 v223, s[22:23]
	global_load_dwordx4 v[150:153], v223, s[22:23] offset:64
	s_add_u32 s100, s100, 0x80
	s_addc_u32 s101, s101, 0
	s_add_u32 s22, s22, 0x80
	s_addc_u32 s23, s23, 0
	s_waitcnt lgkmcnt(1)
	v_mfma_f32_16x16x32_bf16 v[70:73], v[210:213], v[166:169], v[70:73]
	v_mfma_f32_16x16x32_bf16 v[38:41], v[210:213], v[170:173], v[38:41]
	v_mfma_f32_16x16x32_bf16 v[22:25], v[210:213], v[174:177], v[22:25]
	v_mfma_f32_16x16x32_bf16 v[6:9], v[210:213], v[178:181], v[6:9]
	s_waitcnt lgkmcnt(0)
	s_barrier
; #define BLOADG(kt) do { \
;     _Pragma("unroll") for (int i = 0; i < 2; ++i) ra[i] = *(const u32x4*)(ap + (size_t)(64 * i) * lda + (kt) * 32); \
;     _Pragma("unroll") for (int i = 0; i < 4; ++i) rb[i] = *(const u32x4*)(bp + (size_t)((i & 1) * s1 + (i >> 1) * s2) * ldb + (kt) * 32); } while (0)
; #define BSTOREG(st) do { \
;     _Pragma("unroll") for (int i = 0; i < 2; ++i) *(u32x4*)(sA + (st) * BGA + so + 64 * i * 32) = ra[i]; \
;     _Pragma("unroll") for (int i = 0; i < 4; ++i) *(u32x4*)(sB + (st) * BGB + so + 64 * i * 32) = rb[i]; } while (0)
;     ...
;   for (int kt = 0; kt < nk; ++kt) {
;     const int cur = kt & 1;
;     if (kt + 1 < nk) { BSTOREG(cur ^ 1); if (kt + 2 < nk) BLOADG(kt + 2); }
;     const bf16_t* cA = sA + cur * BGA + (wm * 64) * 32 + fo; const bf16_t* cB = sB + cur * BGB + (wn * 128) * 32 + fo;
;     bf16x8 af[4];
; #pragma unroll
;     for (int mi = 0; mi < 4; ++mi) af[mi] = *(const bf16x8*)(cA + mi * 16 * 32);
; #pragma unroll
;     for (int nh = 0; nh < 2; ++nh) {
;       bf16x8 bfr[4];
; #pragma unroll
;       for (int ni = 0; ni < 4; ++ni) bfr[ni] = *(const bf16x8*)(cB + (nh * 4 + ni) * 16 * 32);
; #pragma unroll
;       for (int mi = 0; mi < 4; ++mi)
; #pragma unroll
;         for (int ni = 0; ni < 4; ++ni) acc[mi][nh * 4 + ni] = __builtin_amdgcn_mfma_f32_16x16x32_bf16(bfr[ni], af[mi], acc[mi][nh * 4 + ni], 0, 0, 0);
;     }
;     __syncthreads();
	v_mfma_f32_16x16x32_bf16 v[66:69], v[214:217], v[166:169], v[66:69]
	v_mfma_f32_16x16x32_bf16 v[34:37], v[214:217], v[170:173], v[34:37]
	v_mfma_f32_16x16x32_bf16 v[18:21], v[214:217], v[174:177], v[18:21]
	v_mfma_f32_16x16x32_bf16 v[2:5], v[214:217], v[178:181], v[2:5]
	ds_read_b128 v[166:169], v163 offset:8192
	ds_read_b128 v[170:173], v163 offset:9216
	ds_read_b128 v[174:177], v163 offset:10240
	ds_read_b128 v[178:181], v163 offset:11264
	ds_read_b128 v[182:185], v162 offset:32768
	ds_read_b128 v[206:209], v162 offset:33792
	ds_read_b128 v[210:213], v162 offset:34816
	ds_read_b128 v[214:217], v162 offset:35840
	s_waitcnt lgkmcnt(7)
	s_waitcnt lgkmcnt(3)
	v_mfma_f32_16x16x32_bf16 v[126:129], v[182:185], v[166:169], v[126:129]
	v_mfma_f32_16x16x32_bf16 v[110:113], v[182:185], v[170:173], v[110:113]
	v_mfma_f32_16x16x32_bf16 v[94:97], v[182:185], v[174:177], v[94:97]
	v_mfma_f32_16x16x32_bf16 v[62:65], v[182:185], v[178:181], v[62:65]
	ds_read_b128 v[182:185], v162 offset:36864
	s_waitcnt lgkmcnt(3)
	v_mfma_f32_16x16x32_bf16 v[122:125], v[206:209], v[166:169], v[122:125]
	v_mfma_f32_16x16x32_bf16 v[106:109], v[206:209], v[170:173], v[106:109]
	v_mfma_f32_16x16x32_bf16 v[90:93], v[206:209], v[174:177], v[90:93]
	v_mfma_f32_16x16x32_bf16 v[58:61], v[206:209], v[178:181], v[58:61]
	ds_read_b128 v[206:209], v162 offset:37888
	s_waitcnt lgkmcnt(3)
	v_mfma_f32_16x16x32_bf16 v[118:121], v[210:213], v[166:169], v[118:121]
	v_mfma_f32_16x16x32_bf16 v[102:105], v[210:213], v[170:173], v[102:105]
	v_mfma_f32_16x16x32_bf16 v[82:85], v[210:213], v[174:177], v[82:85]
	v_mfma_f32_16x16x32_bf16 v[50:53], v[210:213], v[178:181], v[50:53]
	ds_read_b128 v[210:213], v162 offset:38912
	s_waitcnt lgkmcnt(3)
	v_mfma_f32_16x16x32_bf16 v[114:117], v[214:217], v[166:169], v[114:117]
	v_mfma_f32_16x16x32_bf16 v[98:101], v[214:217], v[170:173], v[98:101]
	v_mfma_f32_16x16x32_bf16 v[74:77], v[214:217], v[174:177], v[74:77]
	v_mfma_f32_16x16x32_bf16 v[42:45], v[214:217], v[178:181], v[42:45]
	ds_read_b128 v[214:217], v162 offset:39936
	s_waitcnt lgkmcnt(3)
	v_mfma_f32_16x16x32_bf16 v[86:89], v[182:185], v[166:169], v[86:89]
	v_mfma_f32_16x16x32_bf16 v[54:57], v[182:185], v[170:173], v[54:57]
	v_mfma_f32_16x16x32_bf16 v[30:33], v[182:185], v[174:177], v[30:33]
	v_mfma_f32_16x16x32_bf16 v[14:17], v[182:185], v[178:181], v[14:17]
	s_waitcnt vmcnt(0)
	s_waitcnt lgkmcnt(2)
	v_mfma_f32_16x16x32_bf16 v[78:81], v[206:209], v[166:169], v[78:81]
	ds_write_b128 v225, v[134:137] offset:0
	v_mfma_f32_16x16x32_bf16 v[46:49], v[206:209], v[170:173], v[46:49]
	ds_write_b128 v225, v[130:133] offset:4096
	v_mfma_f32_16x16x32_bf16 v[26:29], v[206:209], v[174:177], v[26:29]
	ds_write_b128 v225, v[146:149] offset:16384
	v_mfma_f32_16x16x32_bf16 v[10:13], v[206:209], v[178:181], v[10:13]
	ds_write_b128 v225, v[142:145] offset:20480
	s_waitcnt lgkmcnt(5)
	v_mfma_f32_16x16x32_bf16 v[70:73], v[210:213], v[166:169], v[70:73]
	ds_write_b128 v225, v[138:141] offset:24576
	v_mfma_f32_16x16x32_bf16 v[38:41], v[210:213], v[170:173], v[38:41]
	ds_write_b128 v225, v[150:153] offset:28672
	v_mfma_f32_16x16x32_bf16 v[22:25], v[210:213], v[174:177], v[22:25]
	v_mfma_f32_16x16x32_bf16 v[6:9], v[210:213], v[178:181], v[6:9]
	s_waitcnt lgkmcnt(0)
	s_barrier
	v_mfma_f32_16x16x32_bf16 v[66:69], v[214:217], v[166:169], v[66:69]
	v_mfma_f32_16x16x32_bf16 v[34:37], v[214:217], v[170:173], v[34:37]
	v_mfma_f32_16x16x32_bf16 v[18:21], v[214:217], v[174:177], v[18:21]
	v_mfma_f32_16x16x32_bf16 v[2:5], v[214:217], v[178:181], v[2:5]
	ds_read_b128 v[166:169], v224 offset:33792
	ds_read_b128 v[170:173], v224 offset:34816
	ds_read_b128 v[174:177], v224 offset:35840
	ds_read_b128 v[178:181], v224 offset:36864
	ds_read_b128 v[182:185], v162 offset:49152
	ds_read_b128 v[206:209], v162 offset:50176
	ds_read_b128 v[210:213], v162 offset:51200
	ds_read_b128 v[214:217], v162 offset:52224
	s_waitcnt lgkmcnt(7)
	s_waitcnt lgkmcnt(3)
	v_mfma_f32_16x16x32_bf16 v[126:129], v[182:185], v[166:169], v[126:129]
	v_mfma_f32_16x16x32_bf16 v[110:113], v[182:185], v[170:173], v[110:113]
	v_mfma_f32_16x16x32_bf16 v[94:97], v[182:185], v[174:177], v[94:97]
	v_mfma_f32_16x16x32_bf16 v[62:65], v[182:185], v[178:181], v[62:65]
	ds_read_b128 v[182:185], v162 offset:53248
	s_sub_u32 m0, m0, 0xd000
	s_nop 0
	global_load_lds_dwordx4 v218, s[100:101]
	global_load_dwordx4 v[134:137], v218, s[100:101] offset:64
	s_waitcnt lgkmcnt(3)
	v_mfma_f32_16x16x32_bf16 v[122:125], v[206:209], v[166:169], v[122:125]
	v_mfma_f32_16x16x32_bf16 v[106:109], v[206:209], v[170:173], v[106:109]
	v_mfma_f32_16x16x32_bf16 v[90:93], v[206:209], v[174:177], v[90:93]
	v_mfma_f32_16x16x32_bf16 v[58:61], v[206:209], v[178:181], v[58:61]
	ds_read_b128 v[206:209], v162 offset:54272
	s_add_u32 m0, m0, 0x1000
	s_nop 0
	global_load_lds_dwordx4 v219, s[100:101]
	global_load_dwordx4 v[130:133], v219, s[100:101] offset:64
	s_waitcnt lgkmcnt(3)
	v_mfma_f32_16x16x32_bf16 v[118:121], v[210:213], v[166:169], v[118:121]
	v_mfma_f32_16x16x32_bf16 v[102:105], v[210:213], v[170:173], v[102:105]
	v_mfma_f32_16x16x32_bf16 v[82:85], v[210:213], v[174:177], v[82:85]
	v_mfma_f32_16x16x32_bf16 v[50:53], v[210:213], v[178:181], v[50:53]
	ds_read_b128 v[210:213], v162 offset:55296
	s_add_u32 m0, m0, 0x5000
	s_nop 0
	global_load_lds_dwordx4 v220, s[22:23]
	global_load_dwordx4 v[146:149], v220, s[22:23] offset:64
	s_waitcnt lgkmcnt(3)
	v_mfma_f32_16x16x32_bf16 v[114:117], v[214:217], v[166:169], v[114:117]
	v_mfma_f32_16x16x32_bf16 v[98:101], v[214:217], v[170:173], v[98:101]
	v_mfma_f32_16x16x32_bf16 v[74:77], v[214:217], v[174:177], v[74:77]
	v_mfma_f32_16x16x32_bf16 v[42:45], v[214:217], v[178:181], v[42:45]
	ds_read_b128 v[214:217], v162 offset:56320
	s_add_u32 m0, m0, 0x1000
	s_nop 0
	global_load_lds_dwordx4 v221, s[22:23]
	global_load_dwordx4 v[142:145], v221, s[22:23] offset:64
	s_waitcnt lgkmcnt(3)
; #define BLOADG(kt) do { \
;     _Pragma("unroll") for (int i = 0; i < 2; ++i) ra[i] = *(const u32x4*)(ap + (size_t)(64 * i) * lda + (kt) * 32); \
;     _Pragma("unroll") for (int i = 0; i < 4; ++i) rb[i] = *(const u32x4*)(bp + (size_t)((i & 1) * s1 + (i >> 1) * s2) * ldb + (kt) * 32); } while (0)
; #define BSTOREG(st) do { \
;     _Pragma("unroll") for (int i = 0; i < 2; ++i) *(u32x4*)(sA + (st) * BGA + so + 64 * i * 32) = ra[i]; \
;     _Pragma("unroll") for (int i = 0; i < 4; ++i) *(u32x4*)(sB + (st) * BGB + so + 64 * i * 32) = rb[i]; } while (0)
;     ...
;   for (int kt = 0; kt < nk; ++kt) {
;     const int cur = kt & 1;
;     if (kt + 1 < nk) { BSTOREG(cur ^ 1); if (kt + 2 < nk) BLOADG(kt + 2); }
;     const bf16_t* cA = sA + cur * BGA + (wm * 64) * 32 + fo; const bf16_t* cB = sB + cur * BGB + (wn * 128) * 32 + fo;
;     bf16x8 af[4];
; #pragma unroll
;     for (int mi = 0; mi < 4; ++mi) af[mi] = *(const bf16x8*)(cA + mi * 16 * 32);
; #pragma unroll
;     for (int nh = 0; nh < 2; ++nh) {
;       bf16x8 bfr[4];
; #pragma unroll
;       for (int ni = 0; ni < 4; ++ni) bfr[ni] = *(const bf16x8*)(cB + (nh * 4 + ni) * 16 * 32);
; #pragma unroll
;       for (int mi = 0; mi < 4; ++mi)
; #pragma unroll
;         for (int ni = 0; ni < 4; ++ni) acc[mi][nh * 4 + ni] = __builtin_amdgcn_mfma_f32_16x16x32_bf16(bfr[ni], af[mi], acc[mi][nh * 4 + ni], 0, 0, 0);
;     }
;     __syncthreads();
	v_mfma_f32_16x16x32_bf16 v[86:89], v[182:185], v[166:169], v[86:89]
	v_mfma_f32_16x16x32_bf16 v[54:57], v[182:185], v[170:173], v[54:57]
	v_mfma_f32_16x16x32_bf16 v[30:33], v[182:185], v[174:177], v[30:33]
	v_mfma_f32_16x16x32_bf16 v[14:17], v[182:185], v[178:181], v[14:17]
	s_add_u32 m0, m0, 0x1000
	s_nop 0
	global_load_lds_dwordx4 v222, s[22:23]
	global_load_dwordx4 v[138:141], v222, s[22:23] offset:64
	s_waitcnt lgkmcnt(2)
	v_mfma_f32_16x16x32_bf16 v[78:81], v[206:209], v[166:169], v[78:81]
	v_mfma_f32_16x16x32_bf16 v[46:49], v[206:209], v[170:173], v[46:49]
	v_mfma_f32_16x16x32_bf16 v[26:29], v[206:209], v[174:177], v[26:29]
	v_mfma_f32_16x16x32_bf16 v[10:13], v[206:209], v[178:181], v[10:13]
	s_add_u32 m0, m0, 0x1000
	s_nop 0
	global_load_lds_dwordx4 v223, s[22:23]
	global_load_dwordx4 v[150:153], v223, s[22:23] offset:64
	s_add_u32 s100, s100, 0x80
	s_addc_u32 s101, s101, 0
	s_add_u32 s22, s22, 0x80
	s_addc_u32 s23, s23, 0
	s_waitcnt lgkmcnt(1)
	v_mfma_f32_16x16x32_bf16 v[70:73], v[210:213], v[166:169], v[70:73]
	v_mfma_f32_16x16x32_bf16 v[38:41], v[210:213], v[170:173], v[38:41]
	v_mfma_f32_16x16x32_bf16 v[22:25], v[210:213], v[174:177], v[22:25]
	v_mfma_f32_16x16x32_bf16 v[6:9], v[210:213], v[178:181], v[6:9]
	s_waitcnt lgkmcnt(0)
	s_barrier
	v_mfma_f32_16x16x32_bf16 v[66:69], v[214:217], v[166:169], v[66:69]
	v_mfma_f32_16x16x32_bf16 v[34:37], v[214:217], v[170:173], v[34:37]
	v_mfma_f32_16x16x32_bf16 v[18:21], v[214:217], v[174:177], v[18:21]
	v_mfma_f32_16x16x32_bf16 v[2:5], v[214:217], v[178:181], v[2:5]
	ds_read_b128 v[166:169], v163 offset:0
	ds_read_b128 v[170:173], v163 offset:1024
	ds_read_b128 v[174:177], v163 offset:2048
	ds_read_b128 v[178:181], v163 offset:3072
	ds_read_b128 v[182:185], v162 offset:16384
	ds_read_b128 v[206:209], v162 offset:17408
	ds_read_b128 v[210:213], v162 offset:18432
	ds_read_b128 v[214:217], v162 offset:19456
	s_waitcnt lgkmcnt(7)
	s_waitcnt lgkmcnt(3)
	v_mfma_f32_16x16x32_bf16 v[126:129], v[182:185], v[166:169], v[126:129]
	v_mfma_f32_16x16x32_bf16 v[110:113], v[182:185], v[170:173], v[110:113]
	v_mfma_f32_16x16x32_bf16 v[94:97], v[182:185], v[174:177], v[94:97]
	v_mfma_f32_16x16x32_bf16 v[62:65], v[182:185], v[178:181], v[62:65]
	ds_read_b128 v[182:185], v162 offset:20480
	s_waitcnt lgkmcnt(3)
	v_mfma_f32_16x16x32_bf16 v[122:125], v[206:209], v[166:169], v[122:125]
	v_mfma_f32_16x16x32_bf16 v[106:109], v[206:209], v[170:173], v[106:109]
	v_mfma_f32_16x16x32_bf16 v[90:93], v[206:209], v[174:177], v[90:93]
	v_mfma_f32_16x16x32_bf16 v[58:61], v[206:209], v[178:181], v[58:61]
	ds_read_b128 v[206:209], v162 offset:21504
	s_waitcnt lgkmcnt(3)
	v_mfma_f32_16x16x32_bf16 v[118:121], v[210:213], v[166:169], v[118:121]
	v_mfma_f32_16x16x32_bf16 v[102:105], v[210:213], v[170:173], v[102:105]
	v_mfma_f32_16x16x32_bf16 v[82:85], v[210:213], v[174:177], v[82:85]
	v_mfma_f32_16x16x32_bf16 v[50:53], v[210:213], v[178:181], v[50:53]
	ds_read_b128 v[210:213], v162 offset:22528
	s_waitcnt lgkmcnt(3)
	v_mfma_f32_16x16x32_bf16 v[114:117], v[214:217], v[166:169], v[114:117]
	v_mfma_f32_16x16x32_bf16 v[98:101], v[214:217], v[170:173], v[98:101]
	v_mfma_f32_16x16x32_bf16 v[74:77], v[214:217], v[174:177], v[74:77]
	v_mfma_f32_16x16x32_bf16 v[42:45], v[214:217], v[178:181], v[42:45]
	ds_read_b128 v[214:217], v162 offset:23552
	s_waitcnt lgkmcnt(3)
	v_mfma_f32_16x16x32_bf16 v[86:89], v[182:185], v[166:169], v[86:89]
	v_mfma_f32_16x16x32_bf16 v[54:57], v[182:185], v[170:173], v[54:57]
	v_mfma_f32_16x16x32_bf16 v[30:33], v[182:185], v[174:177], v[30:33]
	v_mfma_f32_16x16x32_bf16 v[14:17], v[182:185], v[178:181], v[14:17]
	s_waitcnt vmcnt(0)
	s_waitcnt lgkmcnt(2)
	v_mfma_f32_16x16x32_bf16 v[78:81], v[206:209], v[166:169], v[78:81]
	ds_write_b128 v226, v[134:137] offset:33792
	v_mfma_f32_16x16x32_bf16 v[46:49], v[206:209], v[170:173], v[46:49]
	ds_write_b128 v226, v[130:133] offset:37888
	v_mfma_f32_16x16x32_bf16 v[26:29], v[206:209], v[174:177], v[26:29]
	ds_write_b128 v225, v[146:149] offset:49152
	v_mfma_f32_16x16x32_bf16 v[10:13], v[206:209], v[178:181], v[10:13]
	ds_write_b128 v225, v[142:145] offset:53248
	s_waitcnt lgkmcnt(5)
	v_mfma_f32_16x16x32_bf16 v[70:73], v[210:213], v[166:169], v[70:73]
	ds_write_b128 v225, v[138:141] offset:57344
	v_mfma_f32_16x16x32_bf16 v[38:41], v[210:213], v[170:173], v[38:41]
	ds_write_b128 v226, v[150:153] offset:28672
	v_mfma_f32_16x16x32_bf16 v[22:25], v[210:213], v[174:177], v[22:25]
	v_mfma_f32_16x16x32_bf16 v[6:9], v[210:213], v[178:181], v[6:9]
	s_waitcnt lgkmcnt(0)
	s_barrier
; #define BLOADG(kt) do { \
;     _Pragma("unroll") for (int i = 0; i < 2; ++i) ra[i] = *(const u32x4*)(ap + (size_t)(64 * i) * lda + (kt) * 32); \
;     _Pragma("unroll") for (int i = 0; i < 4; ++i) rb[i] = *(const u32x4*)(bp + (size_t)((i & 1) * s1 + (i >> 1) * s2) * ldb + (kt) * 32); } while (0)
; #define BSTOREG(st) do { \
;     _Pragma("unroll") for (int i = 0; i < 2; ++i) *(u32x4*)(sA + (st) * BGA + so + 64 * i * 32) = ra[i]; \
;     _Pragma("unroll") for (int i = 0; i < 4; ++i) *(u32x4*)(sB + (st) * BGB + so + 64 * i * 32) = rb[i]; } while (0)
;     ...
;   for (int kt = 0; kt < nk; ++kt) {
;     const int cur = kt & 1;
;     if (kt + 1 < nk) { BSTOREG(cur ^ 1); if (kt + 2 < nk) BLOADG(kt + 2); }
;     const bf16_t* cA = sA + cur * BGA + (wm * 64) * 32 + fo; const bf16_t* cB = sB + cur * BGB + (wn * 128) * 32 + fo;
;     bf16x8 af[4];
; #pragma unroll
;     for (int mi = 0; mi < 4; ++mi) af[mi] = *(const bf16x8*)(cA + mi * 16 * 32);
; #pragma unroll
;     for (int nh = 0; nh < 2; ++nh) {
;       bf16x8 bfr[4];
; #pragma unroll
;       for (int ni = 0; ni < 4; ++ni) bfr[ni] = *(const bf16x8*)(cB + (nh * 4 + ni) * 16 * 32);
; #pragma unroll
;       for (int mi = 0; mi < 4; ++mi)
; #pragma unroll
;         for (int ni = 0; ni < 4; ++ni) acc[mi][nh * 4 + ni] = __builtin_amdgcn_mfma_f32_16x16x32_bf16(bfr[ni], af[mi], acc[mi][nh * 4 + ni], 0, 0, 0);
;     }
;     __syncthreads();
	v_mfma_f32_16x16x32_bf16 v[66:69], v[214:217], v[166:169], v[66:69]
	v_mfma_f32_16x16x32_bf16 v[34:37], v[214:217], v[170:173], v[34:37]
	v_mfma_f32_16x16x32_bf16 v[18:21], v[214:217], v[174:177], v[18:21]
	v_mfma_f32_16x16x32_bf16 v[2:5], v[214:217], v[178:181], v[2:5]
	ds_read_b128 v[166:169], v163 offset:8192
	ds_read_b128 v[170:173], v163 offset:9216
	ds_read_b128 v[174:177], v163 offset:10240
	ds_read_b128 v[178:181], v163 offset:11264
	ds_read_b128 v[182:185], v162 offset:32768
	ds_read_b128 v[206:209], v162 offset:33792
	ds_read_b128 v[210:213], v162 offset:34816
	ds_read_b128 v[214:217], v162 offset:35840
	s_waitcnt lgkmcnt(7)
	s_waitcnt lgkmcnt(3)
	v_mfma_f32_16x16x32_bf16 v[126:129], v[182:185], v[166:169], v[126:129]
	v_mfma_f32_16x16x32_bf16 v[110:113], v[182:185], v[170:173], v[110:113]
	v_mfma_f32_16x16x32_bf16 v[94:97], v[182:185], v[174:177], v[94:97]
	v_mfma_f32_16x16x32_bf16 v[62:65], v[182:185], v[178:181], v[62:65]
	ds_read_b128 v[182:185], v162 offset:36864
	s_sub_u32 m0, m0, 0xb000
	s_nop 0
	global_load_lds_dwordx4 v218, s[100:101]
	global_load_dwordx4 v[134:137], v218, s[100:101] offset:64
	s_waitcnt lgkmcnt(3)
	v_mfma_f32_16x16x32_bf16 v[122:125], v[206:209], v[166:169], v[122:125]
	v_mfma_f32_16x16x32_bf16 v[106:109], v[206:209], v[170:173], v[106:109]
	v_mfma_f32_16x16x32_bf16 v[90:93], v[206:209], v[174:177], v[90:93]
	v_mfma_f32_16x16x32_bf16 v[58:61], v[206:209], v[178:181], v[58:61]
	ds_read_b128 v[206:209], v162 offset:37888
	s_add_u32 m0, m0, 0x1000
	s_nop 0
	global_load_lds_dwordx4 v219, s[100:101]
	global_load_dwordx4 v[130:133], v219, s[100:101] offset:64
	s_waitcnt lgkmcnt(3)
	v_mfma_f32_16x16x32_bf16 v[118:121], v[210:213], v[166:169], v[118:121]
	v_mfma_f32_16x16x32_bf16 v[102:105], v[210:213], v[170:173], v[102:105]
	v_mfma_f32_16x16x32_bf16 v[82:85], v[210:213], v[174:177], v[82:85]
	v_mfma_f32_16x16x32_bf16 v[50:53], v[210:213], v[178:181], v[50:53]
	ds_read_b128 v[210:213], v162 offset:38912
	s_add_u32 m0, m0, 0x3000
	s_nop 0
	global_load_lds_dwordx4 v220, s[22:23]
	global_load_dwordx4 v[146:149], v220, s[22:23] offset:64
	s_waitcnt lgkmcnt(3)
	v_mfma_f32_16x16x32_bf16 v[114:117], v[214:217], v[166:169], v[114:117]
	v_mfma_f32_16x16x32_bf16 v[98:101], v[214:217], v[170:173], v[98:101]
	v_mfma_f32_16x16x32_bf16 v[74:77], v[214:217], v[174:177], v[74:77]
	v_mfma_f32_16x16x32_bf16 v[42:45], v[214:217], v[178:181], v[42:45]
	ds_read_b128 v[214:217], v162 offset:39936
	s_add_u32 m0, m0, 0x1000
	s_nop 0
	global_load_lds_dwordx4 v221, s[22:23]
	global_load_dwordx4 v[142:145], v221, s[22:23] offset:64
	s_waitcnt lgkmcnt(3)
	v_mfma_f32_16x16x32_bf16 v[86:89], v[182:185], v[166:169], v[86:89]
	v_mfma_f32_16x16x32_bf16 v[54:57], v[182:185], v[170:173], v[54:57]
	v_mfma_f32_16x16x32_bf16 v[30:33], v[182:185], v[174:177], v[30:33]
	v_mfma_f32_16x16x32_bf16 v[14:17], v[182:185], v[178:181], v[14:17]
	s_add_u32 m0, m0, 0x1000
	s_nop 0
	global_load_lds_dwordx4 v222, s[22:23]
	global_load_dwordx4 v[138:141], v222, s[22:23] offset:64
	s_waitcnt lgkmcnt(2)
	v_mfma_f32_16x16x32_bf16 v[78:81], v[206:209], v[166:169], v[78:81]
	v_mfma_f32_16x16x32_bf16 v[46:49], v[206:209], v[170:173], v[46:49]
	v_mfma_f32_16x16x32_bf16 v[26:29], v[206:209], v[174:177], v[26:29]
	v_mfma_f32_16x16x32_bf16 v[10:13], v[206:209], v[178:181], v[10:13]
	s_add_u32 m0, m0, 0x1000
	s_nop 0
	global_load_lds_dwordx4 v223, s[22:23]
	global_load_dwordx4 v[150:153], v223, s[22:23] offset:64
	s_add_u32 s100, s100, 0x80
	s_addc_u32 s101, s101, 0
	s_add_u32 s22, s22, 0x80
	s_addc_u32 s23, s23, 0
	s_waitcnt lgkmcnt(1)
	v_mfma_f32_16x16x32_bf16 v[70:73], v[210:213], v[166:169], v[70:73]
	v_mfma_f32_16x16x32_bf16 v[38:41], v[210:213], v[170:173], v[38:41]
	v_mfma_f32_16x16x32_bf16 v[22:25], v[210:213], v[174:177], v[22:25]
	v_mfma_f32_16x16x32_bf16 v[6:9], v[210:213], v[178:181], v[6:9]
	s_waitcnt lgkmcnt(0)
	s_barrier
	v_mfma_f32_16x16x32_bf16 v[66:69], v[214:217], v[166:169], v[66:69]
	v_mfma_f32_16x16x32_bf16 v[34:37], v[214:217], v[170:173], v[34:37]
	v_mfma_f32_16x16x32_bf16 v[18:21], v[214:217], v[174:177], v[18:21]
	v_mfma_f32_16x16x32_bf16 v[2:5], v[214:217], v[178:181], v[2:5]
	ds_read_b128 v[166:169], v224 offset:33792
	ds_read_b128 v[170:173], v224 offset:34816
	ds_read_b128 v[174:177], v224 offset:35840
	ds_read_b128 v[178:181], v224 offset:36864
	ds_read_b128 v[182:185], v162 offset:49152
	ds_read_b128 v[206:209], v162 offset:50176
	ds_read_b128 v[210:213], v162 offset:51200
	ds_read_b128 v[214:217], v162 offset:52224
	s_waitcnt lgkmcnt(7)
	s_waitcnt lgkmcnt(3)
	v_mfma_f32_16x16x32_bf16 v[126:129], v[182:185], v[166:169], v[126:129]
	v_mfma_f32_16x16x32_bf16 v[110:113], v[182:185], v[170:173], v[110:113]
	v_mfma_f32_16x16x32_bf16 v[94:97], v[182:185], v[174:177], v[94:97]
	v_mfma_f32_16x16x32_bf16 v[62:65], v[182:185], v[178:181], v[62:65]
	ds_read_b128 v[182:185], v162 offset:53248
	s_waitcnt lgkmcnt(3)
	v_mfma_f32_16x16x32_bf16 v[122:125], v[206:209], v[166:169], v[122:125]
	v_mfma_f32_16x16x32_bf16 v[106:109], v[206:209], v[170:173], v[106:109]
	v_mfma_f32_16x16x32_bf16 v[90:93], v[206:209], v[174:177], v[90:93]
	v_mfma_f32_16x16x32_bf16 v[58:61], v[206:209], v[178:181], v[58:61]
	ds_read_b128 v[206:209], v162 offset:54272
	s_waitcnt lgkmcnt(3)
	v_mfma_f32_16x16x32_bf16 v[118:121], v[210:213], v[166:169], v[118:121]
	v_mfma_f32_16x16x32_bf16 v[102:105], v[210:213], v[170:173], v[102:105]
	v_mfma_f32_16x16x32_bf16 v[82:85], v[210:213], v[174:177], v[82:85]
	v_mfma_f32_16x16x32_bf16 v[50:53], v[210:213], v[178:181], v[50:53]
	ds_read_b128 v[210:213], v162 offset:55296
	s_waitcnt lgkmcnt(3)
; DI unsigned pack2(float a, float b) { f2_t v = {a, b}; bf2_t r = __builtin_convertvector(v, bf2_t); return __builtin_bit_cast(unsigned, r); }
; DI float frcp(float x) { return __builtin_amdgcn_rcpf(x); }
; #define BLOADG(kt) do { \
;     _Pragma("unroll") for (int i = 0; i < 2; ++i) ra[i] = *(const u32x4*)(ap + (size_t)(64 * i) * lda + (kt) * 32); \
;     _Pragma("unroll") for (int i = 0; i < 4; ++i) rb[i] = *(const u32x4*)(bp + (size_t)((i & 1) * s1 + (i >> 1) * s2) * ldb + (kt) * 32); } while (0)
; #define BSTOREG(st) do { \
;     _Pragma("unroll") for (int i = 0; i < 2; ++i) *(u32x4*)(sA + (st) * BGA + so + 64 * i * 32) = ra[i]; \
;     _Pragma("unroll") for (int i = 0; i < 4; ++i) *(u32x4*)(sB + (st) * BGB + so + 64 * i * 32) = rb[i]; } while (0)
;     ...
;   for (int kt = 0; kt < nk; ++kt) {
;     const int cur = kt & 1;
;     if (kt + 1 < nk) { BSTOREG(cur ^ 1); if (kt + 2 < nk) BLOADG(kt + 2); }
;     const bf16_t* cA = sA + cur * BGA + (wm * 64) * 32 + fo; const bf16_t* cB = sB + cur * BGB + (wn * 128) * 32 + fo;
;     bf16x8 af[4];
; #pragma unroll
;     for (int mi = 0; mi < 4; ++mi) af[mi] = *(const bf16x8*)(cA + mi * 16 * 32);
; #pragma unroll
;     for (int nh = 0; nh < 2; ++nh) {
;       bf16x8 bfr[4];
; #pragma unroll
;       for (int ni = 0; ni < 4; ++ni) bfr[ni] = *(const bf16x8*)(cB + (nh * 4 + ni) * 16 * 32);
; #pragma unroll
;       for (int mi = 0; mi < 4; ++mi)
; #pragma unroll
;         for (int ni = 0; ni < 4; ++ni) acc[mi][nh * 4 + ni] = __builtin_amdgcn_mfma_f32_16x16x32_bf16(bfr[ni], af[mi], acc[mi][nh * 4 + ni], 0, 0, 0);
;     }
;     __syncthreads();
; DI void merge_tile(const Params& p, int l, int tile, char* smem) {
;     ...
; #pragma unroll
;     for (int mi = 0; mi < 4; ++mi)
; #pragma unroll
;       for (int ni = 0; ni < 8; ++ni) {
;         float s0 = frcp(1.0f + __builtin_amdgcn_exp2f(accG[mi][ni][0])), s1 = frcp(1.0f + __builtin_amdgcn_exp2f(accG[mi][ni][1]));
;         float s2 = frcp(1.0f + __builtin_amdgcn_exp2f(accG[mi][ni][2])), s3 = frcp(1.0f + __builtin_amdgcn_exp2f(accG[mi][ni][3]));
;         sg[mi][ni][0] = pack2(s0, s1); sg[mi][ni][1] = pack2(s2, s3);
;       }
	v_mfma_f32_16x16x32_bf16 v[114:117], v[214:217], v[166:169], v[114:117]
	v_mfma_f32_16x16x32_bf16 v[98:101], v[214:217], v[170:173], v[98:101]
	v_mfma_f32_16x16x32_bf16 v[74:77], v[214:217], v[174:177], v[74:77]
	v_mfma_f32_16x16x32_bf16 v[42:45], v[214:217], v[178:181], v[42:45]
	ds_read_b128 v[214:217], v162 offset:56320
	s_waitcnt lgkmcnt(3)
	v_mfma_f32_16x16x32_bf16 v[86:89], v[182:185], v[166:169], v[86:89]
	v_mfma_f32_16x16x32_bf16 v[54:57], v[182:185], v[170:173], v[54:57]
	v_mfma_f32_16x16x32_bf16 v[30:33], v[182:185], v[174:177], v[30:33]
	v_mfma_f32_16x16x32_bf16 v[14:17], v[182:185], v[178:181], v[14:17]
	s_waitcnt vmcnt(0)
	s_waitcnt lgkmcnt(2)
	v_mfma_f32_16x16x32_bf16 v[78:81], v[206:209], v[166:169], v[78:81]
	ds_write_b128 v225, v[134:137] offset:8192
	v_mfma_f32_16x16x32_bf16 v[46:49], v[206:209], v[170:173], v[46:49]
	ds_write_b128 v225, v[130:133] offset:12288
	v_mfma_f32_16x16x32_bf16 v[26:29], v[206:209], v[174:177], v[26:29]
	ds_write_b128 v225, v[146:149] offset:32768
	v_mfma_f32_16x16x32_bf16 v[10:13], v[206:209], v[178:181], v[10:13]
	ds_write_b128 v225, v[142:145] offset:36864
	s_waitcnt lgkmcnt(5)
	v_mfma_f32_16x16x32_bf16 v[70:73], v[210:213], v[166:169], v[70:73]
	ds_write_b128 v225, v[138:141] offset:40960
	v_mfma_f32_16x16x32_bf16 v[38:41], v[210:213], v[170:173], v[38:41]
	ds_write_b128 v225, v[150:153] offset:45056
	v_mfma_f32_16x16x32_bf16 v[22:25], v[210:213], v[174:177], v[22:25]
	v_mfma_f32_16x16x32_bf16 v[6:9], v[210:213], v[178:181], v[6:9]
	s_waitcnt lgkmcnt(0)
	s_barrier
	v_mfma_f32_16x16x32_bf16 v[66:69], v[214:217], v[166:169], v[66:69]
	v_mfma_f32_16x16x32_bf16 v[34:37], v[214:217], v[170:173], v[34:37]
	v_mfma_f32_16x16x32_bf16 v[18:21], v[214:217], v[174:177], v[18:21]
	v_mfma_f32_16x16x32_bf16 v[2:5], v[214:217], v[178:181], v[2:5]
	s_add_i32 s7, s7, 1
	s_cmp_lg_u32 s7, 5
	s_cbranch_scc1 .LBB0_45
	ds_read_b128 v[130:133], v163
	ds_read_b128 v[134:137], v163 offset:1024
	ds_read_b128 v[138:141], v163 offset:2048
	ds_read_b128 v[142:145], v163 offset:3072
	ds_read_b128 v[146:149], v162 offset:16384
	ds_read_b128 v[150:153], v162 offset:17408
	ds_read_b128 v[154:157], v162 offset:18432
	ds_read_b128 v[158:161], v162 offset:19456
	s_mul_i32 s94, s6, 0x130000
	s_waitcnt lgkmcnt(3)
	v_mfma_f32_16x16x32_bf16 v[126:129], v[146:149], v[130:133], v[126:129]
	s_lshl_b64 s[0:1], s[0:1], 9
	s_mov_b32 s6, 4
	s_mov_b64 s[22:23], s[94:95]
	s_waitcnt lgkmcnt(2)
	v_mfma_f32_16x16x32_bf16 v[122:125], v[150:153], v[130:133], v[122:125]
	s_mov_b32 s11, 0x6ca5000
	v_mfma_f32_16x16x32_bf16 v[164:167], v[146:149], v[134:137], v[110:113]
	v_mfma_f32_16x16x32_bf16 v[106:109], v[150:153], v[134:137], v[106:109]
	v_mfma_f32_16x16x32_bf16 v[168:171], v[146:149], v[138:141], v[94:97]
	v_mfma_f32_16x16x32_bf16 v[172:175], v[150:153], v[138:141], v[90:93]
	v_mfma_f32_16x16x32_bf16 v[146:149], v[146:149], v[142:145], v[62:65]
	v_mfma_f32_16x16x32_bf16 v[150:153], v[150:153], v[142:145], v[58:61]
	s_nop 2
	ds_read_b128 v[58:61], v162 offset:20480
	ds_read_b128 v[62:65], v162 offset:21504
	ds_read_b128 v[90:93], v162 offset:22528
	ds_read_b128 v[94:97], v162 offset:23552
	s_waitcnt lgkmcnt(0)
	s_barrier
	v_mfma_f32_16x16x32_bf16 v[118:121], v[154:157], v[130:133], v[118:121]
	v_mfma_f32_16x16x32_bf16 v[114:117], v[158:161], v[130:133], v[114:117]
	v_mfma_f32_16x16x32_bf16 v[102:105], v[154:157], v[134:137], v[102:105]
	v_mfma_f32_16x16x32_bf16 v[98:101], v[158:161], v[134:137], v[98:101]
	v_mfma_f32_16x16x32_bf16 v[82:85], v[154:157], v[138:141], v[82:85]
	v_mfma_f32_16x16x32_bf16 v[74:77], v[158:161], v[138:141], v[74:77]
	v_mfma_f32_16x16x32_bf16 v[50:53], v[154:157], v[142:145], v[50:53]
	v_mfma_f32_16x16x32_bf16 v[42:45], v[158:161], v[142:145], v[42:45]
	v_mfma_f32_16x16x32_bf16 v[154:157], v[58:61], v[130:133], v[86:89]
	v_mfma_f32_16x16x32_bf16 v[158:161], v[62:65], v[130:133], v[78:81]
	v_mfma_f32_16x16x32_bf16 v[70:73], v[90:93], v[130:133], v[70:73]
	v_mfma_f32_16x16x32_bf16 v[66:69], v[94:97], v[130:133], v[66:69]
	v_mfma_f32_16x16x32_bf16 v[130:133], v[58:61], v[134:137], v[54:57]
	v_mfma_f32_16x16x32_bf16 v[176:179], v[62:65], v[134:137], v[46:49]
	v_mfma_f32_16x16x32_bf16 v[38:41], v[90:93], v[134:137], v[38:41]
	v_mfma_f32_16x16x32_bf16 v[34:37], v[94:97], v[134:137], v[34:37]
	v_mfma_f32_16x16x32_bf16 v[134:137], v[58:61], v[138:141], v[30:33]
	v_mfma_f32_16x16x32_bf16 v[180:183], v[62:65], v[138:141], v[26:29]
	v_mfma_f32_16x16x32_bf16 v[184:187], v[90:93], v[138:141], v[22:25]
	v_mfma_f32_16x16x32_bf16 v[18:21], v[94:97], v[138:141], v[18:21]
	v_mfma_f32_16x16x32_bf16 v[138:141], v[58:61], v[142:145], v[14:17]
	v_mfma_f32_16x16x32_bf16 v[10:13], v[62:65], v[142:145], v[10:13]
	v_mfma_f32_16x16x32_bf16 v[6:9], v[90:93], v[142:145], v[6:9]
	v_mfma_f32_16x16x32_bf16 v[2:5], v[94:97], v[142:145], v[2:5]
	ds_read_b128 v[142:145], v163 offset:8192
	ds_read_b128 v[194:197], v163 offset:9216
	ds_read_b128 v[206:209], v163 offset:10240
	ds_read_b128 v[210:213], v163 offset:11264
	ds_read_b128 v[14:17], v162 offset:32768
	ds_read_b128 v[22:25], v162 offset:33792
	ds_read_b128 v[214:217], v162 offset:34816
	ds_read_b128 v[218:221], v162 offset:35840
	s_waitcnt lgkmcnt(3)
	v_mfma_f32_16x16x32_bf16 v[94:97], v[14:17], v[194:197], v[164:167]
	v_mfma_f32_16x16x32_bf16 v[62:65], v[14:17], v[206:209], v[168:171]
	v_mfma_f32_16x16x32_bf16 v[30:33], v[14:17], v[210:213], v[146:149]
	s_nop 5
	v_exp_f32_e32 v94, v94
	v_exp_f32_e32 v62, v62
	v_add_f32_e32 v94, 1.0, v94
	s_waitcnt lgkmcnt(2)
; DI unsigned pack2(float a, float b) { f2_t v = {a, b}; bf2_t r = __builtin_convertvector(v, bf2_t); return __builtin_bit_cast(unsigned, r); }
; DI float frcp(float x) { return __builtin_amdgcn_rcpf(x); }
; DI void merge_tile(const Params& p, int l, int tile, char* smem) {
;     ...
; #pragma unroll
;     for (int mi = 0; mi < 4; ++mi)
; #pragma unroll
;       for (int ni = 0; ni < 8; ++ni) {
;         float s0 = frcp(1.0f + __builtin_amdgcn_exp2f(accG[mi][ni][0])), s1 = frcp(1.0f + __builtin_amdgcn_exp2f(accG[mi][ni][1]));
;         float s2 = frcp(1.0f + __builtin_amdgcn_exp2f(accG[mi][ni][2])), s3 = frcp(1.0f + __builtin_amdgcn_exp2f(accG[mi][ni][3]));
;         sg[mi][ni][0] = pack2(s0, s1); sg[mi][ni][1] = pack2(s2, s3);
;       }
	v_mfma_f32_16x16x32_bf16 v[26:29], v[22:25], v[210:213], v[150:153]
	ds_read_b128 v[146:149], v162 offset:36864
	s_nop 1
	ds_read_b128 v[150:153], v162 offset:37888
	ds_read_b128 v[164:167], v162 offset:38912
	ds_read_b128 v[168:171], v162 offset:39936
	v_add_f32_e32 v62, 1.0, v62
	v_exp_f32_e32 v30, v30
	v_mfma_f32_16x16x32_bf16 v[90:93], v[22:25], v[194:197], v[106:109]
	v_exp_f32_e32 v31, v31
	v_exp_f32_e32 v32, v32
	v_exp_f32_e32 v33, v33
	s_waitcnt lgkmcnt(2)
	v_mfma_f32_16x16x32_bf16 v[106:109], v[150:153], v[142:145], v[158:161]
	v_exp_f32_e32 v26, v26
	s_nop 1
	v_exp_f32_e32 v90, v90
	v_exp_f32_e32 v27, v27
	v_mfma_f32_16x16x32_bf16 v[54:57], v[214:217], v[206:209], v[82:85]
	v_exp_f32_e32 v28, v28
	s_nop 0
	v_exp_f32_e32 v106, v106
	v_add_f32_e32 v90, 1.0, v90
	v_mfma_f32_16x16x32_bf16 v[82:85], v[146:149], v[194:197], v[130:133]
	v_exp_f32_e32 v29, v29
	v_add_f32_e32 v106, 1.0, v106
	v_rcp_f32_e32 v159, v106
	v_exp_f32_e32 v106, v107
	v_mfma_f32_16x16x32_bf16 v[126:129], v[14:17], v[142:145], v[126:129]
	s_nop 2
	v_exp_f32_e32 v82, v82
	v_exp_f32_e32 v54, v54
	v_add_f32_e32 v106, 1.0, v106
	v_mfma_f32_16x16x32_bf16 v[86:89], v[214:217], v[194:197], v[102:105]
	v_add_f32_e32 v82, 1.0, v82
	v_exp_f32_e32 v0, v126
	v_exp_f32_e32 v126, v127
	v_mfma_f32_16x16x32_bf16 v[14:17], v[218:221], v[210:213], v[42:45]
	v_add_f32_e32 v54, 1.0, v54
	s_nop 2
	v_exp_f32_e32 v86, v86
	v_add_f32_e32 v126, 1.0, v126
	s_waitcnt lgkmcnt(1)
	v_mfma_f32_16x16x32_bf16 v[102:105], v[164:167], v[142:145], v[70:73]
	v_rcp_f32_e32 v158, v126
	v_exp_f32_e32 v14, v14
	v_exp_f32_e32 v126, v128
	v_mfma_f32_16x16x32_bf16 v[70:73], v[164:167], v[194:197], v[38:41]
	v_exp_f32_e32 v87, v87
	v_add_f32_e32 v14, 1.0, v14
	v_rcp_f32_e32 v130, v14
	v_mfma_f32_16x16x32_bf16 v[42:45], v[150:153], v[206:209], v[180:183]
	v_exp_f32_e32 v14, v15
	s_nop 2
	v_exp_f32_e32 v70, v70
	v_add_f32_e32 v126, 1.0, v126
	v_mfma_f32_16x16x32_bf16 v[38:41], v[164:167], v[206:209], v[184:187]
	v_rcp_f32_e32 v181, v82
	v_exp_f32_e32 v82, v83
	v_add_f32_e32 v70, 1.0, v70
	v_mfma_f32_16x16x32_bf16 v[6:9], v[164:167], v[210:213], v[6:9]
	v_rcp_f32_e32 v164, v106
	v_exp_f32_e32 v106, v108
	v_add_f32_e32 v82, 1.0, v82
	v_mfma_f32_16x16x32_bf16 v[46:49], v[218:221], v[206:209], v[74:77]
	v_rcp_f32_e32 v182, v82
	v_add_f32_e32 v106, 1.0, v106
	v_rcp_f32_e32 v163, v106
	v_exp_f32_e32 v106, v109
	v_exp_f32_e32 v82, v84
	s_nop 2
	v_exp_f32_e32 v46, v46
	v_mfma_f32_16x16x32_bf16 v[122:125], v[22:25], v[142:145], v[122:125]
	v_add_f32_e32 v106, 1.0, v106
	v_add_f32_e32 v82, 1.0, v82
	v_add_f32_e32 v46, 1.0, v46
	v_mfma_f32_16x16x32_bf16 v[110:113], v[218:221], v[142:145], v[114:117]
	v_rcp_f32_e32 v166, v106
	s_nop 2
	v_exp_f32_e32 v122, v122
	v_rcp_f32_e32 v183, v82
	v_mfma_f32_16x16x32_bf16 v[114:117], v[146:149], v[142:145], v[154:157]
	v_exp_f32_e32 v82, v85
	v_rcp_f32_e32 v106, v46
	v_exp_f32_e32 v46, v47
	v_add_f32_e32 v122, 1.0, v122
	v_add_f32_e32 v82, 1.0, v82
	s_nop 2
	v_exp_f32_e32 v114, v114
	v_add_f32_e32 v46, 1.0, v46
	v_add_f32_e32 v14, 1.0, v14
	v_mfma_f32_16x16x32_bf16 v[78:81], v[218:221], v[194:197], v[98:101]
	v_add_f32_e32 v114, 1.0, v114
	v_rcp_f32_e32 v165, v122
	v_exp_f32_e32 v122, v123
	v_mfma_f32_16x16x32_bf16 v[58:61], v[22:25], v[206:209], v[172:175]
	v_rcp_f32_e32 v184, v82
	v_rcp_f32_e32 v82, v70
	v_exp_f32_e32 v70, v71
	s_waitcnt lgkmcnt(0)
	v_mfma_f32_16x16x32_bf16 v[98:101], v[168:171], v[142:145], v[66:69]
	v_rcp_f32_e32 v175, v90
	v_exp_f32_e32 v90, v91
	v_rcp_f32_e32 v107, v46
	v_mfma_f32_16x16x32_bf16 v[74:77], v[150:153], v[194:197], v[176:179]
	v_exp_f32_e32 v46, v48
	v_rcp_f32_e32 v131, v14
	v_exp_f32_e32 v14, v16
	v_mfma_f32_16x16x32_bf16 v[66:69], v[168:171], v[194:197], v[34:37]
	v_rcp_f32_e32 v177, v114
	v_exp_f32_e32 v114, v115
	v_add_f32_e32 v122, 1.0, v122
	v_mfma_f32_16x16x32_bf16 v[34:37], v[168:171], v[206:209], v[18:21]
	v_add_f32_e32 v90, 1.0, v90
	v_add_f32_e32 v114, 1.0, v114
	v_add_f32_e32 v70, 1.0, v70
	v_mfma_f32_16x16x32_bf16 v[2:5], v[168:171], v[210:213], v[2:5]
	v_rcp_f32_e32 v171, v94
	v_exp_f32_e32 v94, v95
	v_add_f32_e32 v46, 1.0, v46
	v_add_f32_e32 v14, 1.0, v14
	v_rcp_f32_e32 v168, v122
	v_add_f32_e32 v94, 1.0, v94
	v_exp_f32_e32 v122, v124
	v_rcp_f32_e32 v178, v114
	v_exp_f32_e32 v114, v116
	v_rcp_f32_e32 v172, v94
	v_exp_f32_e32 v94, v96
	v_rcp_f32_e32 v176, v90
	v_exp_f32_e32 v90, v92
	v_rcp_f32_e32 v83, v70
	v_exp_f32_e32 v70, v72
	v_rcp_f32_e32 v108, v46
	v_exp_f32_e32 v46, v49
	v_rcp_f32_e32 v132, v14
	v_exp_f32_e32 v14, v17
	v_mfma_f32_16x16x32_bf16 v[22:25], v[214:217], v[210:213], v[50:53]
	v_add_f32_e32 v122, 1.0, v122
	v_add_f32_e32 v114, 1.0, v114
	v_add_f32_e32 v94, 1.0, v94
	v_mfma_f32_16x16x32_bf16 v[50:53], v[146:149], v[206:209], v[134:137]
	v_add_f32_e32 v90, 1.0, v90
	v_add_f32_e32 v70, 1.0, v70
	v_add_f32_e32 v46, 1.0, v46
	v_mfma_f32_16x16x32_bf16 v[18:21], v[146:149], v[210:213], v[138:141]
	v_add_f32_e32 v14, 1.0, v14
	v_rcp_f32_e32 v160, v126
	v_exp_f32_e32 v126, v129
	v_mfma_f32_16x16x32_bf16 v[10:13], v[150:153], v[210:213], v[10:13]
	v_rcp_f32_e32 v169, v122
	v_exp_f32_e32 v122, v125
	v_rcp_f32_e32 v162, v114
	v_exp_f32_e32 v114, v117
	v_rcp_f32_e32 v173, v94
	v_exp_f32_e32 v94, v97
	v_rcp_f32_e32 v179, v90
	v_exp_f32_e32 v90, v93
	v_exp_f32_e32 v75, v75
	v_rcp_f32_e32 v84, v70
	v_exp_f32_e32 v70, v73
	v_exp_f32_e32 v66, v66
	v_exp_f32_e32 v58, v58
	v_rcp_f32_e32 v109, v46
	v_exp_f32_e32 v46, v50
	v_exp_f32_e32 v42, v42
	v_exp_f32_e32 v38, v38
	v_exp_f32_e32 v34, v34
	v_exp_f32_e32 v22, v22
	v_rcp_f32_e32 v133, v14
	v_exp_f32_e32 v14, v18
	v_exp_f32_e32 v10, v10
	v_exp_f32_e32 v6, v6
	v_exp_f32_e32 v2, v2
; DI unsigned pack2(float a, float b) { f2_t v = {a, b}; bf2_t r = __builtin_convertvector(v, bf2_t); return __builtin_bit_cast(unsigned, r); }
; DI float frcp(float x) { return __builtin_amdgcn_rcpf(x); }
; DI void merge_tile(const Params& p, int l, int tile, char* smem) {
;     ...
; #pragma unroll
;     for (int mi = 0; mi < 4; ++mi)
; #pragma unroll
;       for (int ni = 0; ni < 8; ++ni) {
;         float s0 = frcp(1.0f + __builtin_amdgcn_exp2f(accG[mi][ni][0])), s1 = frcp(1.0f + __builtin_amdgcn_exp2f(accG[mi][ni][1]));
;         float s2 = frcp(1.0f + __builtin_amdgcn_exp2f(accG[mi][ni][2])), s3 = frcp(1.0f + __builtin_amdgcn_exp2f(accG[mi][ni][3]));
;         sg[mi][ni][0] = pack2(s0, s1); sg[mi][ni][1] = pack2(s2, s3);
;       }
	v_add_f32_e32 v126, 1.0, v126
	v_add_f32_e32 v122, 1.0, v122
	v_add_f32_e32 v114, 1.0, v114
	v_add_f32_e32 v94, 1.0, v94
	v_add_f32_e32 v90, 1.0, v90
	v_add_f32_e32 v75, 1.0, v75
	v_add_f32_e32 v70, 1.0, v70
	v_add_f32_e32 v66, 1.0, v66
	v_add_f32_e32 v58, 1.0, v58
	v_add_f32_e32 v46, 1.0, v46
	v_add_f32_e32 v42, 1.0, v42
	v_add_f32_e32 v38, 1.0, v38
	v_add_f32_e32 v34, 1.0, v34
	v_add_f32_e32 v22, 1.0, v22
	v_add_f32_e32 v14, 1.0, v14
	v_add_f32_e32 v10, 1.0, v10
	v_add_f32_e32 v6, 1.0, v6
	v_add_f32_e32 v2, 1.0, v2
	v_mfma_f32_16x16x32_bf16 v[118:121], v[214:217], v[142:145], v[118:121]
	v_rcp_f32_e32 v161, v126
	v_rcp_f32_e32 v170, v122
	v_rcp_f32_e32 v167, v114
	v_rcp_f32_e32 v174, v94
	v_rcp_f32_e32 v180, v90
	v_rcp_f32_e32 v185, v75
	v_exp_f32_e32 v75, v76
	v_exp_f32_e32 v76, v77
	v_rcp_f32_e32 v85, v70
	v_rcp_f32_e32 v90, v66
	v_exp_f32_e32 v66, v67
	v_rcp_f32_e32 v70, v62
	v_exp_f32_e32 v62, v63
	v_rcp_f32_e32 v77, v58
	v_exp_f32_e32 v58, v59
	v_rcp_f32_e32 v94, v54
	v_exp_f32_e32 v54, v55
	v_rcp_f32_e32 v210, v46
	v_exp_f32_e32 v46, v51
	v_rcp_f32_e32 v214, v42
	v_exp_f32_e32 v42, v43
	v_rcp_f32_e32 v114, v38
	v_exp_f32_e32 v38, v39
	v_rcp_f32_e32 v122, v34
	v_exp_f32_e32 v34, v35
	v_rcp_f32_e32 v126, v22
	v_exp_f32_e32 v22, v23
	v_rcp_f32_e32 v137, v14
	v_exp_f32_e32 v14, v19
	v_rcp_f32_e32 v143, v10
	v_exp_f32_e32 v10, v11
	v_rcp_f32_e32 v134, v6
	v_exp_f32_e32 v6, v7
	v_rcp_f32_e32 v144, v2
	v_exp_f32_e32 v2, v3
	v_add_f32_e32 v66, 1.0, v66
	v_add_f32_e32 v62, 1.0, v62
	v_add_f32_e32 v58, 1.0, v58
	v_add_f32_e32 v54, 1.0, v54
	v_add_f32_e32 v46, 1.0, v46
	v_add_f32_e32 v42, 1.0, v42
	v_add_f32_e32 v38, 1.0, v38
	v_add_f32_e32 v34, 1.0, v34
	v_add_f32_e32 v22, 1.0, v22
	v_add_f32_e32 v14, 1.0, v14
	v_add_f32_e32 v10, 1.0, v10
	v_add_f32_e32 v6, 1.0, v6
	v_add_f32_e32 v2, 1.0, v2
	v_rcp_f32_e32 v91, v66
	v_exp_f32_e32 v66, v68
	v_rcp_f32_e32 v71, v62
	v_exp_f32_e32 v62, v64
	v_rcp_f32_e32 v207, v58
	v_exp_f32_e32 v58, v60
	v_rcp_f32_e32 v95, v54
	v_exp_f32_e32 v54, v56
	v_rcp_f32_e32 v211, v46
	v_exp_f32_e32 v46, v52
	v_rcp_f32_e32 v215, v42
	v_exp_f32_e32 v42, v44
	v_rcp_f32_e32 v115, v38
	v_exp_f32_e32 v38, v40
	v_rcp_f32_e32 v123, v34
	v_exp_f32_e32 v34, v36
	v_rcp_f32_e32 v127, v22
	v_exp_f32_e32 v22, v24
	v_rcp_f32_e32 v139, v14
	v_exp_f32_e32 v14, v20
	v_rcp_f32_e32 v142, v10
	v_exp_f32_e32 v10, v12
	v_rcp_f32_e32 v136, v6
	v_exp_f32_e32 v6, v8
	v_rcp_f32_e32 v146, v2
	v_exp_f32_e32 v2, v4
	v_add_f32_e32 v66, 1.0, v66
	v_add_f32_e32 v62, 1.0, v62
	v_add_f32_e32 v58, 1.0, v58
	v_add_f32_e32 v54, 1.0, v54
	v_add_f32_e32 v46, 1.0, v46
	v_add_f32_e32 v42, 1.0, v42
	v_add_f32_e32 v38, 1.0, v38
	v_add_f32_e32 v34, 1.0, v34
	v_add_f32_e32 v22, 1.0, v22
	v_add_f32_e32 v14, 1.0, v14
	v_add_f32_e32 v10, 1.0, v10
	v_add_f32_e32 v6, 1.0, v6
	v_add_f32_e32 v2, 1.0, v2
	v_exp_f32_e32 v118, v118
	v_exp_f32_e32 v119, v119
	v_exp_f32_e32 v120, v120
	v_exp_f32_e32 v121, v121
	v_exp_f32_e32 v110, v110
	v_exp_f32_e32 v111, v111
	v_exp_f32_e32 v112, v112
	v_exp_f32_e32 v113, v113
	v_exp_f32_e32 v102, v102
	v_exp_f32_e32 v103, v103
	v_exp_f32_e32 v104, v104
	v_exp_f32_e32 v105, v105
	v_exp_f32_e32 v98, v98
	v_exp_f32_e32 v99, v99
	v_exp_f32_e32 v100, v100
	v_exp_f32_e32 v101, v101
	v_exp_f32_e32 v88, v88
	v_exp_f32_e32 v89, v89
	v_exp_f32_e32 v78, v78
	v_exp_f32_e32 v79, v79
	v_exp_f32_e32 v80, v80
	v_exp_f32_e32 v81, v81
	v_exp_f32_e32 v74, v74
	v_rcp_f32_e32 v92, v66
	v_exp_f32_e32 v66, v69
	v_rcp_f32_e32 v72, v62
	v_exp_f32_e32 v62, v65
	v_rcp_f32_e32 v208, v58
	v_exp_f32_e32 v58, v61
	v_rcp_f32_e32 v96, v54
	v_exp_f32_e32 v54, v57
	v_rcp_f32_e32 v212, v46
	v_exp_f32_e32 v46, v53
	v_rcp_f32_e32 v216, v42
	v_exp_f32_e32 v42, v45
	v_rcp_f32_e32 v116, v38
; DI unsigned pack2(float a, float b) { f2_t v = {a, b}; bf2_t r = __builtin_convertvector(v, bf2_t); return __builtin_bit_cast(unsigned, r); }
; DI float frcp(float x) { return __builtin_amdgcn_rcpf(x); }
; DI void merge_tile(const Params& p, int l, int tile, char* smem) {
;     ...
; #pragma unroll
;     for (int mi = 0; mi < 4; ++mi)
; #pragma unroll
;       for (int ni = 0; ni < 8; ++ni) {
;         float s0 = frcp(1.0f + __builtin_amdgcn_exp2f(accG[mi][ni][0])), s1 = frcp(1.0f + __builtin_amdgcn_exp2f(accG[mi][ni][1]));
;         float s2 = frcp(1.0f + __builtin_amdgcn_exp2f(accG[mi][ni][2])), s3 = frcp(1.0f + __builtin_amdgcn_exp2f(accG[mi][ni][3]));
;         sg[mi][ni][0] = pack2(s0, s1); sg[mi][ni][1] = pack2(s2, s3);
;       }
;   }
;   f32x4 accM[4][2]; zero_acc<2>(accM);
; #pragma unroll 1
;   for (int n = 0; n < 4; ++n) {
;     f32x4 accB[4][2]; zero_acc<2>(accB);
	v_exp_f32_e32 v38, v41
	v_rcp_f32_e32 v124, v34
	v_exp_f32_e32 v34, v37
	v_rcp_f32_e32 v128, v22
	v_exp_f32_e32 v22, v25
	v_rcp_f32_e32 v135, v14
	v_exp_f32_e32 v14, v21
	v_rcp_f32_e32 v145, v10
	v_exp_f32_e32 v10, v13
	v_rcp_f32_e32 v138, v6
	v_exp_f32_e32 v6, v9
	v_rcp_f32_e32 v148, v2
	v_exp_f32_e32 v2, v5
	v_add_f32_e32 v0, 1.0, v0
	v_add_f32_e32 v118, 1.0, v118
	v_add_f32_e32 v119, 1.0, v119
	v_add_f32_e32 v120, 1.0, v120
	v_add_f32_e32 v121, 1.0, v121
	v_add_f32_e32 v110, 1.0, v110
	v_add_f32_e32 v111, 1.0, v111
	v_add_f32_e32 v112, 1.0, v112
	v_add_f32_e32 v113, 1.0, v113
	v_add_f32_e32 v102, 1.0, v102
	v_add_f32_e32 v103, 1.0, v103
	v_add_f32_e32 v104, 1.0, v104
	v_add_f32_e32 v105, 1.0, v105
	v_add_f32_e32 v98, 1.0, v98
	v_add_f32_e32 v99, 1.0, v99
	v_add_f32_e32 v100, 1.0, v100
	v_add_f32_e32 v101, 1.0, v101
	v_add_f32_e32 v86, 1.0, v86
	v_add_f32_e32 v87, 1.0, v87
	v_add_f32_e32 v88, 1.0, v88
	v_add_f32_e32 v89, 1.0, v89
	v_add_f32_e32 v78, 1.0, v78
	v_add_f32_e32 v79, 1.0, v79
	v_add_f32_e32 v80, 1.0, v80
	v_add_f32_e32 v81, 1.0, v81
	v_add_f32_e32 v74, 1.0, v74
	v_add_f32_e32 v75, 1.0, v75
	v_add_f32_e32 v76, 1.0, v76
	v_add_f32_e32 v66, 1.0, v66
	v_add_f32_e32 v62, 1.0, v62
	v_add_f32_e32 v58, 1.0, v58
	v_add_f32_e32 v54, 1.0, v54
	v_add_f32_e32 v46, 1.0, v46
	v_add_f32_e32 v42, 1.0, v42
	v_add_f32_e32 v38, 1.0, v38
	v_add_f32_e32 v34, 1.0, v34
	v_add_f32_e32 v30, 1.0, v30
	v_add_f32_e32 v31, 1.0, v31
	v_add_f32_e32 v32, 1.0, v32
	v_add_f32_e32 v33, 1.0, v33
	v_add_f32_e32 v26, 1.0, v26
	v_add_f32_e32 v27, 1.0, v27
	v_add_f32_e32 v28, 1.0, v28
	v_add_f32_e32 v29, 1.0, v29
	v_add_f32_e32 v22, 1.0, v22
	v_add_f32_e32 v14, 1.0, v14
	v_add_f32_e32 v10, 1.0, v10
	v_add_f32_e32 v6, 1.0, v6
	v_add_f32_e32 v2, 1.0, v2
	v_rcp_f32_e32 v0, v0
	v_rcp_f32_e32 v118, v118
	v_rcp_f32_e32 v119, v119
	v_rcp_f32_e32 v120, v120
	v_rcp_f32_e32 v121, v121
	v_rcp_f32_e32 v110, v110
	v_rcp_f32_e32 v111, v111
	v_rcp_f32_e32 v112, v112
	v_rcp_f32_e32 v113, v113
	v_rcp_f32_e32 v102, v102
	v_rcp_f32_e32 v103, v103
	v_rcp_f32_e32 v104, v104
	v_rcp_f32_e32 v105, v105
	v_rcp_f32_e32 v98, v98
	v_rcp_f32_e32 v99, v99
	v_rcp_f32_e32 v100, v100
	v_rcp_f32_e32 v101, v101
	v_rcp_f32_e32 v86, v86
	v_rcp_f32_e32 v87, v87
	v_rcp_f32_e32 v88, v88
	v_rcp_f32_e32 v89, v89
	v_rcp_f32_e32 v78, v78
	v_rcp_f32_e32 v79, v79
	v_rcp_f32_e32 v80, v80
	v_rcp_f32_e32 v81, v81
	v_rcp_f32_e32 v74, v74
	v_rcp_f32_e32 v75, v75
	v_rcp_f32_e32 v76, v76
	v_rcp_f32_e32 v93, v66
	v_rcp_f32_e32 v73, v62
	v_rcp_f32_e32 v209, v58
	v_rcp_f32_e32 v97, v54
	v_rcp_f32_e32 v213, v46
	v_rcp_f32_e32 v217, v42
	v_rcp_f32_e32 v117, v38
	v_rcp_f32_e32 v125, v34
	v_rcp_f32_e32 v30, v30
	v_rcp_f32_e32 v31, v31
	v_rcp_f32_e32 v32, v32
	v_rcp_f32_e32 v33, v33
	v_rcp_f32_e32 v26, v26
	v_rcp_f32_e32 v27, v27
	v_rcp_f32_e32 v28, v28
	v_rcp_f32_e32 v29, v29
	v_rcp_f32_e32 v129, v22
	v_rcp_f32_e32 v140, v14
	v_rcp_f32_e32 v147, v10
	v_rcp_f32_e32 v141, v6
	v_rcp_f32_e32 v149, v2
	v_mov_b32_e32 v38, 0
	v_mov_b32_e32 v39, v38
	v_mov_b32_e32 v40, v38
	v_mov_b32_e32 v41, v38
	v_mov_b32_e32 v42, v38
	v_mov_b32_e32 v43, v38
	v_mov_b32_e32 v44, v38
	v_mov_b32_e32 v45, v38
	v_mov_b32_e32 v46, v38
	v_mov_b32_e32 v47, v38
	v_mov_b32_e32 v48, v38
	v_mov_b32_e32 v49, v38
	v_mov_b32_e32 v50, v38
	v_mov_b32_e32 v51, v38
	v_mov_b32_e32 v52, v38
	v_mov_b32_e32 v53, v38
	v_mov_b32_e32 v54, v38
	v_mov_b32_e32 v55, v38
	v_mov_b32_e32 v56, v38
	v_mov_b32_e32 v57, v38
	v_mov_b32_e32 v58, v38
	v_mov_b32_e32 v59, v38
	v_mov_b32_e32 v60, v38
	v_mov_b32_e32 v61, v38
	v_mov_b32_e32 v62, v38
	v_mov_b32_e32 v63, v38
	v_mov_b32_e32 v64, v38
	v_mov_b32_e32 v65, v38
	v_mov_b32_e32 v66, v38
	v_mov_b32_e32 v67, v38
	v_mov_b32_e32 v68, v38
	v_mov_b32_e32 v69, v38
	s_barrier

; __global__ void __launch_bounds__(256, 2) mega(Params p, int ph_lo, int ph_hi) {
;   __shared__ __attribute__((aligned(16))) char smem[66048];
;   __shared__ uint4 xb_words;
	.amdhsa_kernel _Z4mega6Paramsii
		.amdhsa_group_segment_fixed_size 74752
		.amdhsa_private_segment_fixed_size 0
		.amdhsa_kernarg_size 392
		.amdhsa_user_sgpr_count 2
		.amdhsa_user_sgpr_dispatch_ptr 0
		.amdhsa_user_sgpr_queue_ptr 0
		.amdhsa_user_sgpr_kernarg_segment_ptr 1
		.amdhsa_user_sgpr_dispatch_id 0
		.amdhsa_user_sgpr_kernarg_preload_length 0
		.amdhsa_user_sgpr_kernarg_preload_offset 0
		.amdhsa_user_sgpr_private_segment_size 0
		.amdhsa_uses_dynamic_stack 0
		.amdhsa_enable_private_segment 0
		.amdhsa_system_sgpr_workgroup_id_x 1
		.amdhsa_system_sgpr_workgroup_id_y 0
		.amdhsa_system_sgpr_workgroup_id_z 0
		.amdhsa_system_sgpr_workgroup_info 0
		.amdhsa_system_vgpr_workitem_id 2
		.amdhsa_next_free_vgpr 256
		.amdhsa_next_free_sgpr 102
		.amdhsa_accum_offset 256
		.amdhsa_reserve_vcc 1
		.amdhsa_float_round_mode_32 0
		.amdhsa_float_round_mode_16_64 0
		.amdhsa_float_denorm_mode_32 3
		.amdhsa_float_denorm_mode_16_64 3
		.amdhsa_dx10_clamp 1
		.amdhsa_ieee_mode 1
		.amdhsa_fp16_overflow 0
		.amdhsa_tg_split 0
		.amdhsa_exception_fp_ieee_invalid_op 0
		.amdhsa_exception_fp_denorm_src 0
		.amdhsa_exception_fp_ieee_div_zero 0
		.amdhsa_exception_fp_ieee_overflow 0
		.amdhsa_exception_fp_ieee_underflow 0
		.amdhsa_exception_fp_ieee_inexact 0
		.amdhsa_exception_int_div_zero 0
	.end_amdhsa_kernel

; __global__ void __launch_bounds__(256, 2) mega(Params p, int ph_lo, int ph_hi) {
;   __shared__ __attribute__((aligned(16))) char smem[66048];
;   __shared__ uint4 xb_words;
amdhsa.kernels:
  - .agpr_count:     0
    .args:
      - .offset:         0
        .size:           128
        .value_kind:     by_value
      - .offset:         128
        .size:           4
        .value_kind:     by_value
      - .offset:         132
        .size:           4
        .value_kind:     by_value
      - .offset:         136
        .size:           4
        .value_kind:     hidden_block_count_x
      - .offset:         140
        .size:           4
        .value_kind:     hidden_block_count_y
      - .offset:         144
        .size:           4
        .value_kind:     hidden_block_count_z
      - .offset:         148
        .size:           2
        .value_kind:     hidden_group_size_x
      - .offset:         150
        .size:           2
        .value_kind:     hidden_group_size_y
      - .offset:         152
        .size:           2
        .value_kind:     hidden_group_size_z
      - .offset:         154
        .size:           2
        .value_kind:     hidden_remainder_x
      - .offset:         156
        .size:           2
        .value_kind:     hidden_remainder_y
      - .offset:         158
        .size:           2
        .value_kind:     hidden_remainder_z
      - .offset:         176
        .size:           8
        .value_kind:     hidden_global_offset_x
      - .offset:         184
        .size:           8
        .value_kind:     hidden_global_offset_y
      - .offset:         192
        .size:           8
        .value_kind:     hidden_global_offset_z
      - .offset:         200
        .size:           2
        .value_kind:     hidden_grid_dims
      - .offset:         224
        .size:           8
        .value_kind:     hidden_multigrid_sync_arg
    .group_segment_fixed_size: 74752
    .kernarg_segment_align: 8
    .kernarg_segment_size: 392
    .language:       OpenCL C
    .language_version:
      - 2
      - 0
    .max_flat_workgroup_size: 256
    .name:           _Z4mega6Paramsii
    .private_segment_fixed_size: 0
    .sgpr_count:     108
    .sgpr_spill_count: 181
    .symbol:         _Z4mega6Paramsii.kd
    .uniform_work_group_size: 1
    .uses_dynamic_stack: false
    .vgpr_count:     256
    .vgpr_spill_count: 0
    .wavefront_size: 64
